# GEMM epilogues: FFN-in ssq loads and residual-stream loads issued together instead of one-by-one behind vmcnt(0)
# speedup vs baseline: 1.0748x; 1.0204x over previous
;     __device__ __forceinline__ void operator()(f32x4 (&acc)[2][2][4][2], const Unit& u, int wr, int wc, int fr, int fq) const {
;         const int lane = fq * 16 + fr;
;         const int rowt = u.pm * 254;
; #pragma unroll
;         for (int ai = 0; ai < 2; ++ai)
; #pragma unroll
;             for (int m = 0; m < 4; ++m) { const int row = rowt + ai * 128 + wr * 64 + m * 16 + fr; const f32x4 pv = *(const f32x4*)(ssq + (size_t)row * 16 + 4 * fq); float sq = (pv[0] + pv[1]) + (pv[2] + pv[3]); sq += __shfl_xor(sq, 16); sq += __shfl_xor(sq, 32);
;                 const float rs = rsqrtf(sq * (1.0f / 1024.0f) + NEPS);
; #pragma unroll
;                 for (int bj = 0; bj < 2; ++bj)
; #pragma unroll
;                     for (int n = 0; n < 2; ++n) acc[ai][bj][m][n] = acc[ai][bj][m][n] * rs;
;                 asm volatile("" ::: "memory"); }
.LBB0_416:
	v_and_b32_e32 v190, 64, v198
	v_xor_b32_e32 v130, 16, v198
	v_add_u32_e32 v131, 64, v190
	v_cmp_lt_i32_e32 vcc, v130, v131
	s_mulk_i32 s2, 0xfe
	v_add_u32_e32 v170, s2, v205
	v_cndmask_b32_e32 v130, v198, v130, vcc
	v_lshlrev_b32_e32 v147, 2, v130
	v_xor_b32_e32 v130, 32, v198
	v_cmp_lt_i32_e32 vcc, v130, v131
	v_ashrrev_i32_e32 v171, 31, v170
	s_mov_b32 s12, 0x3a800000
	v_cndmask_b32_e32 v130, v198, v130, vcc
	v_lshlrev_b32_e32 v146, 2, v130
	s_mov_b32 s24, s97
	s_mov_b32 s15, s96
	v_cmp_lt_i32_e64 s[72:73], 14, v204
	v_lshlrev_b64 v[130:131], 6, v[170:171]
	v_lshl_add_u64 v[130:131], v[154:155], 0, v[130:131]
	global_load_dwordx4 v[130:133], v[130:131], off
	v_add_u32_e32 v134, 0x10, v170
	v_ashrrev_i32_e32 v135, 31, v134
	v_lshlrev_b64 v[134:135], 6, v[134:135]
	v_lshl_add_u64 v[134:135], v[154:155], 0, v[134:135]
	global_load_dwordx4 v[134:137], v[134:135], off
	v_add_u32_e32 v138, 0x20, v170
	v_ashrrev_i32_e32 v139, 31, v138
	v_lshlrev_b64 v[138:139], 6, v[138:139]
	v_lshl_add_u64 v[138:139], v[154:155], 0, v[138:139]
	global_load_dwordx4 v[138:141], v[138:139], off
	v_add_u32_e32 v142, 0x30, v170
	v_ashrrev_i32_e32 v143, 31, v142
	v_lshlrev_b64 v[142:143], 6, v[142:143]
	v_lshl_add_u64 v[142:143], v[154:155], 0, v[142:143]
	global_load_dwordx4 v[142:145], v[142:143], off
	v_add_u32_e32 v160, 0x80, v170
	v_ashrrev_i32_e32 v161, 31, v160
	v_lshlrev_b64 v[160:161], 6, v[160:161]
	v_lshl_add_u64 v[160:161], v[154:155], 0, v[160:161]
	global_load_dwordx4 v[160:163], v[160:161], off
	v_add_u32_e32 v172, 0x90, v170
	v_ashrrev_i32_e32 v173, 31, v172
	v_lshlrev_b64 v[172:173], 6, v[172:173]
	v_lshl_add_u64 v[172:173], v[154:155], 0, v[172:173]
	global_load_dwordx4 v[172:175], v[172:173], off
	v_add_u32_e32 v184, 0xa0, v170
	v_ashrrev_i32_e32 v185, 31, v184
	v_lshlrev_b64 v[184:185], 6, v[184:185]
	v_lshl_add_u64 v[184:185], v[154:155], 0, v[184:185]
	global_load_dwordx4 v[184:187], v[184:185], off
	s_waitcnt vmcnt(6)
	v_add_f32_e32 v130, v131, v130
	v_add_f32_e32 v132, v132, v133
	v_add_f32_e32 v200, v130, v132
	v_add_u32_e32 v130, 0xb0, v170
	v_ashrrev_i32_e32 v131, 31, v130
	v_lshlrev_b64 v[130:131], 6, v[130:131]
	v_lshl_add_u64 v[130:131], v[154:155], 0, v[130:131]
	global_load_dwordx4 v[130:133], v[130:131], off
	s_waitcnt vmcnt(6)
	v_add_f32_e32 v134, v135, v134
	v_add_f32_e32 v136, v136, v137
	v_add_f32_e32 v134, v134, v136
	s_waitcnt vmcnt(5)
	v_add_f32_e32 v138, v139, v138
	v_add_f32_e32 v140, v140, v141
	v_add_f32_e32 v138, v138, v140
	s_waitcnt vmcnt(4)
	v_add_f32_e32 v142, v143, v142
	v_add_f32_e32 v144, v144, v145
	v_add_f32_e32 v142, v142, v144
	s_waitcnt vmcnt(3)
	v_add_f32_e32 v160, v161, v160
	v_add_f32_e32 v162, v162, v163
	v_add_f32_e32 v160, v160, v162
	s_waitcnt vmcnt(2)
	v_add_f32_e32 v172, v173, v172
	v_add_f32_e32 v174, v174, v175
	v_add_f32_e32 v172, v172, v174
	s_waitcnt vmcnt(1)
	v_add_f32_e32 v184, v185, v184
	v_add_f32_e32 v186, v186, v187
	v_add_f32_e32 v184, v184, v186
	s_waitcnt vmcnt(0)
	v_add_f32_e32 v130, v131, v130
	v_add_f32_e32 v132, v132, v133
	v_add_f32_e32 v130, v130, v132
	ds_bpermute_b32 v201, v147, v200
	ds_bpermute_b32 v135, v147, v134
	ds_bpermute_b32 v139, v147, v138
	ds_bpermute_b32 v143, v147, v142
	ds_bpermute_b32 v161, v147, v160
	ds_bpermute_b32 v173, v147, v172
	ds_bpermute_b32 v185, v147, v184
	ds_bpermute_b32 v131, v147, v130
	s_waitcnt lgkmcnt(0)
	v_add_f32_e32 v200, v200, v201
	v_add_f32_e32 v134, v134, v135
	v_add_f32_e32 v138, v138, v139
	v_add_f32_e32 v142, v142, v143
	v_add_f32_e32 v160, v160, v161
	v_add_f32_e32 v172, v172, v173
	v_add_f32_e32 v184, v184, v185
	v_add_f32_e32 v130, v130, v131
	ds_bpermute_b32 v201, v146, v200
	ds_bpermute_b32 v135, v146, v134
	ds_bpermute_b32 v139, v146, v138
	ds_bpermute_b32 v143, v146, v142
	ds_bpermute_b32 v161, v146, v160
	ds_bpermute_b32 v173, v146, v172
	ds_bpermute_b32 v185, v146, v184
	ds_bpermute_b32 v131, v146, v130
	s_waitcnt lgkmcnt(0)
	v_add_f32_e32 v200, v200, v201
	v_add_f32_e32 v134, v134, v135
	v_add_f32_e32 v138, v138, v139
	v_add_f32_e32 v142, v142, v143
	v_add_f32_e32 v160, v160, v161
	v_add_f32_e32 v172, v172, v173
	v_add_f32_e32 v184, v184, v185
	v_add_f32_e32 v130, v130, v131
	v_fma_f32 v175, v184, s12, v196
	v_fma_f32 v184, v134, s12, v196
	v_fma_f32 v185, v200, s12, v196
	v_fma_f32 v187, v138, s12, v196
	v_fma_f32 v186, v142, s12, v196
	v_fma_f32 v173, v160, s12, v196
	v_fma_f32 v172, v172, s12, v196
	v_fma_f32 v174, v130, s12, v196
	v_cmp_gt_f32_e32 vcc, s33, v184
	v_cmp_gt_f32_e64 s[68:69], s33, v185
	v_cmp_gt_f32_e64 s[62:63], s33, v187
	v_cmp_gt_f32_e64 s[70:71], s33, v186
	v_cmp_gt_f32_e64 s[58:59], s33, v172
	v_cmp_gt_f32_e64 s[64:65], s33, v173
	s_mov_b64 s[12:13], 0
	v_cmp_gt_f32_e64 s[60:61], s33, v175
	v_cmp_gt_f32_e64 s[66:67], s33, v174
	s_and_saveexec_b64 s[94:95], s[72:73]
	s_xor_b64 s[72:73], exec, s[94:95]
	s_mov_b64 s[12:13], exec
	s_or_saveexec_b64 s[72:73], s[72:73]
	v_mul_f32_e32 v130, 0x4b800000, v185
	v_cndmask_b32_e64 v130, v185, v130, s[68:69]
	v_rsq_f32_e32 v130, v130
	v_mul_f32_e32 v131, 0x4b800000, v186
	v_cndmask_b32_e64 v131, v186, v131, s[70:71]
	v_rsq_f32_e32 v131, v131
	v_mul_f32_e32 v132, 0x45800000, v130
	v_cndmask_b32_e64 v182, v130, v132, s[68:69]
	v_pk_mul_f32 v[142:143], v[126:127], v[182:183] op_sel_hi:[1,0]
	v_mul_f32_e32 v126, 0x45800000, v131
	v_cndmask_b32_e64 v176, v131, v126, s[70:71]
	v_pk_mul_f32 v[120:121], v[120:121], v[176:177] op_sel_hi:[1,0]
	v_pk_mul_f32 v[116:117], v[116:117], v[176:177] op_sel_hi:[1,0]
	v_pk_mul_f32 v[144:145], v[128:129], v[182:183] op_sel_hi:[1,0]
	v_pk_mul_f32 v[118:119], v[118:119], v[176:177] op_sel_hi:[1,0]
	v_pk_mul_f32 v[114:115], v[114:115], v[176:177] op_sel_hi:[1,0]
	v_readlane_b32 s68, v254, 35
	v_mov_b64_e32 v[128:129], v[116:117]
	v_mov_b64_e32 v[132:133], v[120:121]
	v_pk_mul_f32 v[124:125], v[124:125], v[182:183] op_sel_hi:[1,0]
	v_pk_mul_f32 v[122:123], v[122:123], v[182:183] op_sel_hi:[1,0]
	v_mov_b32_e32 v134, s68
	v_mov_b64_e32 v[126:127], v[114:115]
	v_mov_b64_e32 v[130:131], v[118:119]
	s_xor_b64 exec, exec, s[72:73]
	s_cbranch_execz .LBB0_420
	v_readlane_b32 s68, v254, 36
	s_andn2_b64 s[12:13], s[12:13], exec
	v_mov_b64_e32 v[128:129], v[124:125]
	v_mov_b32_e32 v134, s68
	s_and_b64 s[68:69], s[36:37], exec
	v_mov_b64_e32 v[130:131], v[142:143]
	s_or_b64 s[12:13], s[12:13], s[68:69]
	v_mov_b64_e32 v[126:127], v[122:123]
	v_mov_b64_e32 v[132:133], v[144:145]

;     __device__ __forceinline__ void operator()(const f32x4 (&acc)[2][2][4][2], const Unit& u, int wr, int wc, int fr, int fq) const {
;     ...
;             for (int m = 0; m < 4; ++m) { const int row = row0 + u.pm * 256 + ai * 128 + wr * 64 + m * 16 + fr; const bool pad = row_is_pad(row); float s = 0.f;
; #pragma unroll
;                 for (int bj = 0; bj < 2; ++bj) { const size_t off = (size_t)row * 1024 + col0 + bj * 128; const u32x4 hv = __builtin_nontemporal_load((const u32x4*)(hin + off));
;                     f32x4 v0 = acc[ai][bj][m][0], v1 = acc[ai][bj][m][1];
;                     v0[0] += __uint_as_float(hv.x << 16); v0[1] += __uint_as_float(hv.x & 0xffff0000u); v0[2] += __uint_as_float(hv.y << 16); v0[3] += __uint_as_float(hv.y & 0xffff0000u);
;                     v1[0] += __uint_as_float(hv.z << 16); v1[1] += __uint_as_float(hv.z & 0xffff0000u); v1[2] += __uint_as_float(hv.w << 16); v1[3] += __uint_as_float(hv.w & 0xffff0000u);
.LBB0_546:
	v_lshl_add_u32 v154, s56, 8, v150
	v_lshl_or_b32 v192, s24, 8, v152
	v_ashrrev_i32_e32 v193, 31, v192
	v_add_u32_e32 v164, s61, v154
	v_ashrrev_i32_e32 v165, 31, v164
	v_lshlrev_b64 v[164:165], 10, v[164:165]
	v_lshl_add_u64 v[164:165], v[164:165], 0, v[192:193]
	v_lshl_add_u64 v[164:165], v[164:165], 1, s[4:5]
	global_load_dwordx4 v[160:163], v[164:165], off nt
	global_load_dwordx4 v[164:167], v[164:165], off offset:256 nt
	v_add3_u32 v172, s61, v154, 16
	v_ashrrev_i32_e32 v173, 31, v172
	v_lshlrev_b64 v[172:173], 10, v[172:173]
	v_lshl_add_u64 v[172:173], v[172:173], 0, v[192:193]
	v_lshl_add_u64 v[172:173], v[172:173], 1, s[4:5]
	global_load_dwordx4 v[168:171], v[172:173], off nt
	global_load_dwordx4 v[172:175], v[172:173], off offset:256 nt
	v_add3_u32 v180, s61, v154, 32
	v_ashrrev_i32_e32 v181, 31, v180
	v_lshlrev_b64 v[180:181], 10, v[180:181]
	v_lshl_add_u64 v[180:181], v[180:181], 0, v[192:193]
	v_lshl_add_u64 v[180:181], v[180:181], 1, s[4:5]
	global_load_dwordx4 v[176:179], v[180:181], off nt
	global_load_dwordx4 v[180:183], v[180:181], off offset:256 nt
	v_add3_u32 v188, s61, v154, 48
	v_ashrrev_i32_e32 v189, 31, v188
	v_lshlrev_b64 v[188:189], 10, v[188:189]
	v_lshl_add_u64 v[188:189], v[188:189], 0, v[192:193]
	v_lshl_add_u64 v[188:189], v[188:189], 1, s[4:5]
	global_load_dwordx4 v[184:187], v[188:189], off nt
	global_load_dwordx4 v[188:191], v[188:189], off offset:256 nt
	v_add_u32_e32 v208, s75, v154
	v_ashrrev_i32_e32 v209, 31, v208
	v_lshlrev_b64 v[208:209], 10, v[208:209]
	v_lshl_add_u64 v[208:209], v[208:209], 0, v[192:193]
	v_lshl_add_u64 v[208:209], v[208:209], 1, s[4:5]
	global_load_dwordx4 v[204:207], v[208:209], off nt
	global_load_dwordx4 v[208:211], v[208:209], off offset:256 nt
	v_add_u32_e32 v216, s76, v154
	v_ashrrev_i32_e32 v217, 31, v216
	v_lshlrev_b64 v[216:217], 10, v[216:217]
	v_lshl_add_u64 v[216:217], v[216:217], 0, v[192:193]
	v_lshl_add_u64 v[216:217], v[216:217], 1, s[4:5]
	global_load_dwordx4 v[212:215], v[216:217], off nt
	global_load_dwordx4 v[216:219], v[216:217], off offset:256 nt
	v_add_u32_e32 v236, s77, v154
	v_ashrrev_i32_e32 v237, 31, v236
	v_lshlrev_b64 v[236:237], 10, v[236:237]
	v_lshl_add_u64 v[236:237], v[236:237], 0, v[192:193]
	v_lshl_add_u64 v[236:237], v[236:237], 1, s[4:5]
	global_load_dwordx4 v[232:235], v[236:237], off nt
	global_load_dwordx4 v[236:239], v[236:237], off offset:256 nt
	v_add_u32_e32 v244, s78, v154
	v_ashrrev_i32_e32 v245, 31, v244
	v_lshlrev_b64 v[244:245], 10, v[244:245]
	v_lshl_add_u64 v[244:245], v[244:245], 0, v[192:193]
	v_lshl_add_u64 v[244:245], v[244:245], 1, s[4:5]
	global_load_dwordx4 v[240:243], v[244:245], off nt
	global_load_dwordx4 v[244:247], v[244:245], off offset:256 nt
	s_waitcnt vmcnt(15)
	v_lshlrev_b32_e32 v248, 16, v160
	v_and_b32_e32 v249, 0xffff0000, v160
	v_pk_add_f32 v[126:127], v[126:127], v[248:249]
	v_lshlrev_b32_e32 v250, 16, v161
	v_and_b32_e32 v251, 0xffff0000, v161
	v_pk_add_f32 v[128:129], v[128:129], v[250:251]
	v_lshlrev_b32_e32 v248, 16, v162
	v_and_b32_e32 v249, 0xffff0000, v162
	v_pk_add_f32 v[122:123], v[122:123], v[248:249]
	v_lshlrev_b32_e32 v250, 16, v163
	v_and_b32_e32 v251, 0xffff0000, v163
	v_pk_add_f32 v[124:125], v[124:125], v[250:251]
	s_waitcnt vmcnt(14)
	v_lshlrev_b32_e32 v248, 16, v164
	v_and_b32_e32 v249, 0xffff0000, v164
	v_pk_add_f32 v[118:119], v[118:119], v[248:249]
	v_lshlrev_b32_e32 v250, 16, v165
	v_and_b32_e32 v251, 0xffff0000, v165
	v_pk_add_f32 v[120:121], v[120:121], v[250:251]
	v_lshlrev_b32_e32 v248, 16, v166
	v_and_b32_e32 v249, 0xffff0000, v166
	v_pk_add_f32 v[114:115], v[114:115], v[248:249]
	v_lshlrev_b32_e32 v250, 16, v167
	v_and_b32_e32 v251, 0xffff0000, v167
	v_pk_add_f32 v[116:117], v[116:117], v[250:251]
	s_waitcnt vmcnt(13)
	v_lshlrev_b32_e32 v248, 16, v168
	v_and_b32_e32 v249, 0xffff0000, v168
	v_pk_add_f32 v[110:111], v[110:111], v[248:249]
	v_lshlrev_b32_e32 v250, 16, v169
	v_and_b32_e32 v251, 0xffff0000, v169
	v_pk_add_f32 v[112:113], v[112:113], v[250:251]
	v_lshlrev_b32_e32 v248, 16, v170
	v_and_b32_e32 v249, 0xffff0000, v170
	v_pk_add_f32 v[106:107], v[106:107], v[248:249]
	v_lshlrev_b32_e32 v250, 16, v171
	v_and_b32_e32 v251, 0xffff0000, v171
	v_pk_add_f32 v[108:109], v[108:109], v[250:251]
	s_waitcnt vmcnt(12)
	v_lshlrev_b32_e32 v248, 16, v172
	v_and_b32_e32 v249, 0xffff0000, v172
	v_pk_add_f32 v[102:103], v[102:103], v[248:249]
	v_lshlrev_b32_e32 v250, 16, v173
	v_and_b32_e32 v251, 0xffff0000, v173
	v_pk_add_f32 v[104:105], v[104:105], v[250:251]
	v_lshlrev_b32_e32 v248, 16, v174
	v_and_b32_e32 v249, 0xffff0000, v174
	v_pk_add_f32 v[98:99], v[98:99], v[248:249]
	v_lshlrev_b32_e32 v250, 16, v175
	v_and_b32_e32 v251, 0xffff0000, v175
	v_pk_add_f32 v[100:101], v[100:101], v[250:251]
	s_waitcnt vmcnt(11)
	v_lshlrev_b32_e32 v248, 16, v176
	v_and_b32_e32 v249, 0xffff0000, v176
	v_pk_add_f32 v[94:95], v[94:95], v[248:249]
	v_lshlrev_b32_e32 v250, 16, v177
	v_and_b32_e32 v251, 0xffff0000, v177
	v_pk_add_f32 v[96:97], v[96:97], v[250:251]
	v_lshlrev_b32_e32 v248, 16, v178
	v_and_b32_e32 v249, 0xffff0000, v178
	v_pk_add_f32 v[90:91], v[90:91], v[248:249]
	v_lshlrev_b32_e32 v250, 16, v179
	v_and_b32_e32 v251, 0xffff0000, v179
	v_pk_add_f32 v[92:93], v[92:93], v[250:251]
	s_waitcnt vmcnt(10)
	v_lshlrev_b32_e32 v248, 16, v180
	v_and_b32_e32 v249, 0xffff0000, v180
	v_pk_add_f32 v[86:87], v[86:87], v[248:249]
	v_lshlrev_b32_e32 v250, 16, v181
	v_and_b32_e32 v251, 0xffff0000, v181
	v_pk_add_f32 v[88:89], v[88:89], v[250:251]
	v_lshlrev_b32_e32 v248, 16, v182
	v_and_b32_e32 v249, 0xffff0000, v182
	v_pk_add_f32 v[82:83], v[82:83], v[248:249]
	v_lshlrev_b32_e32 v250, 16, v183
	v_and_b32_e32 v251, 0xffff0000, v183
	v_pk_add_f32 v[84:85], v[84:85], v[250:251]
	s_waitcnt vmcnt(9)
; __device__ __forceinline__ u32x4 pack8(const f32x4 a, const f32x4 b) { u32x4 w; w.x = cvt_pk_bf16(a[0], a[1]); w.y = cvt_pk_bf16(a[2], a[3]); w.z = cvt_pk_bf16(b[0], b[1]); w.w = cvt_pk_bf16(b[2], b[3]); return w; }
;     __device__ __forceinline__ void operator()(const f32x4 (&acc)[2][2][4][2], const Unit& u, int wr, int wc, int fr, int fq) const {
;     ...
;             for (int m = 0; m < 4; ++m) { const int row = row0 + u.pm * 256 + ai * 128 + wr * 64 + m * 16 + fr; const bool pad = row_is_pad(row); float s = 0.f;
; #pragma unroll
;                 for (int bj = 0; bj < 2; ++bj) { const size_t off = (size_t)row * 1024 + col0 + bj * 128; const u32x4 hv = __builtin_nontemporal_load((const u32x4*)(hin + off));
;                     f32x4 v0 = acc[ai][bj][m][0], v1 = acc[ai][bj][m][1];
;                     v0[0] += __uint_as_float(hv.x << 16); v0[1] += __uint_as_float(hv.x & 0xffff0000u); v0[2] += __uint_as_float(hv.y << 16); v0[3] += __uint_as_float(hv.y & 0xffff0000u);
;                     v1[0] += __uint_as_float(hv.z << 16); v1[1] += __uint_as_float(hv.z & 0xffff0000u); v1[2] += __uint_as_float(hv.w << 16); v1[3] += __uint_as_float(hv.w & 0xffff0000u);
; #pragma unroll
;                     for (int e = 0; e < 4; ++e) s += v0[e] * v0[e] + v1[e] * v1[e];
;                     if (!pad) *(u32x4*)(hout + off) = pack8(v0, v1); }
	v_lshlrev_b32_e32 v248, 16, v184
	v_and_b32_e32 v249, 0xffff0000, v184
	v_pk_add_f32 v[78:79], v[78:79], v[248:249]
	v_lshlrev_b32_e32 v250, 16, v185
	v_and_b32_e32 v251, 0xffff0000, v185
	v_pk_add_f32 v[80:81], v[80:81], v[250:251]
	v_lshlrev_b32_e32 v248, 16, v186
	v_and_b32_e32 v249, 0xffff0000, v186
	v_pk_add_f32 v[74:75], v[74:75], v[248:249]
	v_lshlrev_b32_e32 v250, 16, v187
	v_and_b32_e32 v251, 0xffff0000, v187
	v_pk_add_f32 v[76:77], v[76:77], v[250:251]
	s_waitcnt vmcnt(8)
	v_lshlrev_b32_e32 v248, 16, v188
	v_and_b32_e32 v249, 0xffff0000, v188
	v_pk_add_f32 v[70:71], v[70:71], v[248:249]
	v_lshlrev_b32_e32 v250, 16, v189
	v_and_b32_e32 v251, 0xffff0000, v189
	v_pk_add_f32 v[72:73], v[72:73], v[250:251]
	v_lshlrev_b32_e32 v248, 16, v190
	v_and_b32_e32 v249, 0xffff0000, v190
	v_pk_add_f32 v[66:67], v[66:67], v[248:249]
	v_lshlrev_b32_e32 v250, 16, v191
	v_and_b32_e32 v251, 0xffff0000, v191
	v_pk_add_f32 v[68:69], v[68:69], v[250:251]
	s_waitcnt vmcnt(7)
	v_lshlrev_b32_e32 v248, 16, v204
	v_and_b32_e32 v249, 0xffff0000, v204
	v_pk_add_f32 v[62:63], v[62:63], v[248:249]
	v_lshlrev_b32_e32 v250, 16, v205
	v_and_b32_e32 v251, 0xffff0000, v205
	v_pk_add_f32 v[64:65], v[64:65], v[250:251]
	v_lshlrev_b32_e32 v248, 16, v206
	v_and_b32_e32 v249, 0xffff0000, v206
	v_pk_add_f32 v[58:59], v[58:59], v[248:249]
	v_lshlrev_b32_e32 v250, 16, v207
	v_and_b32_e32 v251, 0xffff0000, v207
	v_pk_add_f32 v[60:61], v[60:61], v[250:251]
	s_waitcnt vmcnt(6)
	v_lshlrev_b32_e32 v248, 16, v208
	v_and_b32_e32 v249, 0xffff0000, v208
	v_pk_add_f32 v[54:55], v[54:55], v[248:249]
	v_lshlrev_b32_e32 v250, 16, v209
	v_and_b32_e32 v251, 0xffff0000, v209
	v_pk_add_f32 v[56:57], v[56:57], v[250:251]
	v_lshlrev_b32_e32 v248, 16, v210
	v_and_b32_e32 v249, 0xffff0000, v210
	v_pk_add_f32 v[50:51], v[50:51], v[248:249]
	v_lshlrev_b32_e32 v250, 16, v211
	v_and_b32_e32 v251, 0xffff0000, v211
	v_pk_add_f32 v[52:53], v[52:53], v[250:251]
	s_waitcnt vmcnt(5)
	v_lshlrev_b32_e32 v248, 16, v212
	v_and_b32_e32 v249, 0xffff0000, v212
	v_pk_add_f32 v[46:47], v[46:47], v[248:249]
	v_lshlrev_b32_e32 v250, 16, v213
	v_and_b32_e32 v251, 0xffff0000, v213
	v_pk_add_f32 v[48:49], v[48:49], v[250:251]
	v_lshlrev_b32_e32 v248, 16, v214
	v_and_b32_e32 v249, 0xffff0000, v214
	v_pk_add_f32 v[42:43], v[42:43], v[248:249]
	v_lshlrev_b32_e32 v250, 16, v215
	v_and_b32_e32 v251, 0xffff0000, v215
	v_pk_add_f32 v[44:45], v[44:45], v[250:251]
	s_waitcnt vmcnt(4)
	v_lshlrev_b32_e32 v248, 16, v216
	v_and_b32_e32 v249, 0xffff0000, v216
	v_pk_add_f32 v[38:39], v[38:39], v[248:249]
	v_lshlrev_b32_e32 v250, 16, v217
	v_and_b32_e32 v251, 0xffff0000, v217
	v_pk_add_f32 v[40:41], v[40:41], v[250:251]
	v_lshlrev_b32_e32 v248, 16, v218
	v_and_b32_e32 v249, 0xffff0000, v218
	v_pk_add_f32 v[34:35], v[34:35], v[248:249]
	v_lshlrev_b32_e32 v250, 16, v219
	v_and_b32_e32 v251, 0xffff0000, v219
	v_pk_add_f32 v[36:37], v[36:37], v[250:251]
	s_waitcnt vmcnt(3)
	v_lshlrev_b32_e32 v248, 16, v232
	v_and_b32_e32 v249, 0xffff0000, v232
	v_pk_add_f32 v[30:31], v[30:31], v[248:249]
	v_lshlrev_b32_e32 v250, 16, v233
	v_and_b32_e32 v251, 0xffff0000, v233
	v_pk_add_f32 v[32:33], v[32:33], v[250:251]
	v_lshlrev_b32_e32 v248, 16, v234
	v_and_b32_e32 v249, 0xffff0000, v234
	v_pk_add_f32 v[26:27], v[26:27], v[248:249]
	v_lshlrev_b32_e32 v250, 16, v235
	v_and_b32_e32 v251, 0xffff0000, v235
	v_pk_add_f32 v[28:29], v[28:29], v[250:251]
	s_waitcnt vmcnt(2)
	v_lshlrev_b32_e32 v248, 16, v236
	v_and_b32_e32 v249, 0xffff0000, v236
	v_pk_add_f32 v[22:23], v[22:23], v[248:249]
	v_lshlrev_b32_e32 v250, 16, v237
	v_and_b32_e32 v251, 0xffff0000, v237
	v_pk_add_f32 v[24:25], v[24:25], v[250:251]
	v_lshlrev_b32_e32 v248, 16, v238
	v_and_b32_e32 v249, 0xffff0000, v238
	v_pk_add_f32 v[18:19], v[18:19], v[248:249]
	v_lshlrev_b32_e32 v250, 16, v239
	v_and_b32_e32 v251, 0xffff0000, v239
	v_pk_add_f32 v[20:21], v[20:21], v[250:251]
	s_waitcnt vmcnt(1)
	v_lshlrev_b32_e32 v248, 16, v240
	v_and_b32_e32 v249, 0xffff0000, v240
	v_pk_add_f32 v[14:15], v[14:15], v[248:249]
	v_lshlrev_b32_e32 v250, 16, v241
	v_and_b32_e32 v251, 0xffff0000, v241
	v_pk_add_f32 v[16:17], v[16:17], v[250:251]
	v_lshlrev_b32_e32 v248, 16, v242
	v_and_b32_e32 v249, 0xffff0000, v242
	v_pk_add_f32 v[10:11], v[10:11], v[248:249]
	v_lshlrev_b32_e32 v250, 16, v243
	v_and_b32_e32 v251, 0xffff0000, v243
	v_pk_add_f32 v[12:13], v[12:13], v[250:251]
	s_waitcnt vmcnt(0)
	v_lshlrev_b32_e32 v248, 16, v244
	v_and_b32_e32 v249, 0xffff0000, v244
	v_pk_add_f32 v[6:7], v[6:7], v[248:249]
	v_lshlrev_b32_e32 v250, 16, v245
	v_and_b32_e32 v251, 0xffff0000, v245
	v_pk_add_f32 v[8:9], v[8:9], v[250:251]
	v_lshlrev_b32_e32 v248, 16, v246
	v_and_b32_e32 v249, 0xffff0000, v246
	v_pk_add_f32 v[2:3], v[2:3], v[248:249]
	v_lshlrev_b32_e32 v250, 16, v247
	v_and_b32_e32 v251, 0xffff0000, v247
	v_pk_add_f32 v[4:5], v[4:5], v[250:251]
	v_add_u32_e32 v142, s61, v154
	v_cmp_lt_i32_e32 vcc, s14, v142
	s_mov_b64 s[54:55], -1
	s_mov_b64 s[52:53], -1
	v_mov_b32_e32 v140, v142
	s_and_saveexec_b64 s[12:13], vcc
	s_cbranch_execz .LBB0_552
	v_cmp_lt_u32_e32 vcc, s26, v142
	s_mov_b64 s[52:53], 0
	s_and_saveexec_b64 s[56:57], vcc
	s_xor_b64 s[56:57], exec, s[56:57]
	v_add_u32_e32 v140, 0xffffbf00, v142
	v_cmp_gt_u32_e32 vcc, s81, v140
	s_and_b64 s[52:53], vcc, exec
	s_andn2_saveexec_b64 s[56:57], s[56:57]
	v_add_u32_e32 v140, 0xffffdfc0, v142
	s_or_b64 s[52:53], s[52:53], exec
	s_or_b64 exec, exec, s[56:57]
	s_orn2_b64 s[52:53], s[52:53], exec
.LBB0_552:
	s_or_b64 exec, exec, s[12:13]
	s_and_saveexec_b64 s[12:13], s[52:53]
	v_cmp_gt_i32_e32 vcc, 48, v140
	s_orn2_b64 s[54:55], vcc, exec
	s_or_b64 exec, exec, s[12:13]
	v_lshl_or_b32 v140, s24, 8, v152
	v_ashrrev_i32_e32 v143, 31, v142
	v_ashrrev_i32_e32 v141, 31, v140
	v_lshlrev_b64 v[144:145], 10, v[142:143]
	v_lshl_add_u64 v[156:157], v[144:145], 0, v[140:141]
	v_lshl_add_u64 v[148:149], v[156:157], 1, s[4:5]
	s_nop 1
	s_xor_b64 s[12:13], s[54:55], -1
	v_lshl_add_u64 v[144:145], v[156:157], 1, s[0:1]
	s_and_saveexec_b64 s[52:53], s[12:13]
	s_cbranch_execz .LBB0_556
	v_cvt_pk_bf16_f32 v156, v126, v127
	v_cvt_pk_bf16_f32 v157, v128, v129
	v_cvt_pk_bf16_f32 v158, v122, v123
	v_cvt_pk_bf16_f32 v159, v124, v125
	global_store_dwordx4 v[144:145], v[156:159], off
.LBB0_556:
	s_or_b64 exec, exec, s[52:53]
	s_nop 1
	s_and_saveexec_b64 s[52:53], s[12:13]
	s_cbranch_execz .LBB0_558
	v_cvt_pk_bf16_f32 v146, v118, v119
	v_cvt_pk_bf16_f32 v147, v120, v121
	v_cvt_pk_bf16_f32 v148, v114, v115
	v_cvt_pk_bf16_f32 v149, v116, v117
	global_store_dwordx4 v[144:145], v[146:149], off offset:256

; __device__ __forceinline__ u32x4 pack8(const f32x4 a, const f32x4 b) { u32x4 w; w.x = cvt_pk_bf16(a[0], a[1]); w.y = cvt_pk_bf16(a[2], a[3]); w.z = cvt_pk_bf16(b[0], b[1]); w.w = cvt_pk_bf16(b[2], b[3]); return w; }
;     __device__ __forceinline__ void operator()(const f32x4 (&acc)[2][2][4][2], const Unit& u, int wr, int wc, int fr, int fq) const {
;     ...
;             for (int m = 0; m < 4; ++m) { const int row = row0 + u.pm * 256 + ai * 128 + wr * 64 + m * 16 + fr; const bool pad = row_is_pad(row); float s = 0.f;
; #pragma unroll
;                 for (int bj = 0; bj < 2; ++bj) { const size_t off = (size_t)row * 1024 + col0 + bj * 128; const u32x4 hv = __builtin_nontemporal_load((const u32x4*)(hin + off));
;                     f32x4 v0 = acc[ai][bj][m][0], v1 = acc[ai][bj][m][1];
;                     v0[0] += __uint_as_float(hv.x << 16); v0[1] += __uint_as_float(hv.x & 0xffff0000u); v0[2] += __uint_as_float(hv.y << 16); v0[3] += __uint_as_float(hv.y & 0xffff0000u);
;                     v1[0] += __uint_as_float(hv.z << 16); v1[1] += __uint_as_float(hv.z & 0xffff0000u); v1[2] += __uint_as_float(hv.w << 16); v1[3] += __uint_as_float(hv.w & 0xffff0000u);
; #pragma unroll
;                     for (int e = 0; e < 4; ++e) s += v0[e] * v0[e] + v1[e] * v1[e];
;                     if (!pad) *(u32x4*)(hout + off) = pack8(v0, v1); }
.LBB0_566:
	s_or_b64 exec, exec, s[12:13]
	s_and_saveexec_b64 s[12:13], s[56:57]
	v_cmp_gt_i32_e32 vcc, 48, v115
	s_orn2_b64 s[54:55], vcc, exec
	s_or_b64 exec, exec, s[12:13]
	v_ashrrev_i32_e32 v115, 31, v114
	v_lshlrev_b64 v[116:117], 10, v[114:115]
	v_lshl_add_u64 v[116:117], v[116:117], 0, v[140:141]
	v_lshl_add_u64 v[118:119], v[116:117], 1, s[4:5]
	s_nop 1
	s_xor_b64 s[12:13], s[54:55], -1
	v_lshl_add_u64 v[116:117], v[116:117], 1, s[0:1]
	s_and_saveexec_b64 s[56:57], s[12:13]
	s_cbranch_execz .LBB0_570
	v_cvt_pk_bf16_f32 v122, v110, v111
	v_cvt_pk_bf16_f32 v123, v112, v113
	v_cvt_pk_bf16_f32 v124, v106, v107
	v_cvt_pk_bf16_f32 v125, v108, v109
	global_store_dwordx4 v[116:117], v[122:125], off
.LBB0_570:
	s_or_b64 exec, exec, s[56:57]
	s_nop 1
	s_and_saveexec_b64 s[56:57], s[12:13]
	s_cbranch_execz .LBB0_572
	v_cvt_pk_bf16_f32 v122, v102, v103
	v_cvt_pk_bf16_f32 v123, v104, v105
	v_cvt_pk_bf16_f32 v124, v98, v99
	v_cvt_pk_bf16_f32 v125, v100, v101
	global_store_dwordx4 v[116:117], v[122:125], off offset:256

; __device__ __forceinline__ u32x4 pack8(const f32x4 a, const f32x4 b) { u32x4 w; w.x = cvt_pk_bf16(a[0], a[1]); w.y = cvt_pk_bf16(a[2], a[3]); w.z = cvt_pk_bf16(b[0], b[1]); w.w = cvt_pk_bf16(b[2], b[3]); return w; }
;     __device__ __forceinline__ void operator()(const f32x4 (&acc)[2][2][4][2], const Unit& u, int wr, int wc, int fr, int fq) const {
;     ...
;             for (int m = 0; m < 4; ++m) { const int row = row0 + u.pm * 256 + ai * 128 + wr * 64 + m * 16 + fr; const bool pad = row_is_pad(row); float s = 0.f;
; #pragma unroll
;                 for (int bj = 0; bj < 2; ++bj) { const size_t off = (size_t)row * 1024 + col0 + bj * 128; const u32x4 hv = __builtin_nontemporal_load((const u32x4*)(hin + off));
;                     f32x4 v0 = acc[ai][bj][m][0], v1 = acc[ai][bj][m][1];
;                     v0[0] += __uint_as_float(hv.x << 16); v0[1] += __uint_as_float(hv.x & 0xffff0000u); v0[2] += __uint_as_float(hv.y << 16); v0[3] += __uint_as_float(hv.y & 0xffff0000u);
;                     v1[0] += __uint_as_float(hv.z << 16); v1[1] += __uint_as_float(hv.z & 0xffff0000u); v1[2] += __uint_as_float(hv.w << 16); v1[3] += __uint_as_float(hv.w & 0xffff0000u);
; #pragma unroll
;                     for (int e = 0; e < 4; ++e) s += v0[e] * v0[e] + v1[e] * v1[e];
;                     if (!pad) *(u32x4*)(hout + off) = pack8(v0, v1); }
.LBB0_580:
	s_or_b64 exec, exec, s[12:13]
	s_and_saveexec_b64 s[12:13], s[56:57]
	v_cmp_gt_i32_e32 vcc, 48, v99
	s_orn2_b64 s[54:55], vcc, exec
	s_or_b64 exec, exec, s[12:13]
	v_ashrrev_i32_e32 v99, 31, v98
	v_lshlrev_b64 v[100:101], 10, v[98:99]
	v_lshl_add_u64 v[100:101], v[100:101], 0, v[140:141]
	v_lshl_add_u64 v[102:103], v[100:101], 1, s[4:5]
	s_nop 1
	s_xor_b64 s[12:13], s[54:55], -1
	v_lshl_add_u64 v[100:101], v[100:101], 1, s[0:1]
	s_and_saveexec_b64 s[56:57], s[12:13]
	s_cbranch_execz .LBB0_584
	v_cvt_pk_bf16_f32 v104, v94, v95
	v_cvt_pk_bf16_f32 v105, v96, v97
	v_cvt_pk_bf16_f32 v106, v90, v91
	v_cvt_pk_bf16_f32 v107, v92, v93
	global_store_dwordx4 v[100:101], v[104:107], off
.LBB0_584:
	s_or_b64 exec, exec, s[56:57]
	s_nop 1
	s_and_saveexec_b64 s[56:57], s[12:13]
	s_cbranch_execz .LBB0_586
	v_cvt_pk_bf16_f32 v102, v86, v87
	v_cvt_pk_bf16_f32 v103, v88, v89
	v_cvt_pk_bf16_f32 v104, v82, v83
	v_cvt_pk_bf16_f32 v105, v84, v85
	global_store_dwordx4 v[100:101], v[102:105], off offset:256

; __device__ __forceinline__ u32x4 pack8(const f32x4 a, const f32x4 b) { u32x4 w; w.x = cvt_pk_bf16(a[0], a[1]); w.y = cvt_pk_bf16(a[2], a[3]); w.z = cvt_pk_bf16(b[0], b[1]); w.w = cvt_pk_bf16(b[2], b[3]); return w; }
;     __device__ __forceinline__ void operator()(const f32x4 (&acc)[2][2][4][2], const Unit& u, int wr, int wc, int fr, int fq) const {
;     ...
;             for (int m = 0; m < 4; ++m) { const int row = row0 + u.pm * 256 + ai * 128 + wr * 64 + m * 16 + fr; const bool pad = row_is_pad(row); float s = 0.f;
; #pragma unroll
;                 for (int bj = 0; bj < 2; ++bj) { const size_t off = (size_t)row * 1024 + col0 + bj * 128; const u32x4 hv = __builtin_nontemporal_load((const u32x4*)(hin + off));
;                     f32x4 v0 = acc[ai][bj][m][0], v1 = acc[ai][bj][m][1];
;                     v0[0] += __uint_as_float(hv.x << 16); v0[1] += __uint_as_float(hv.x & 0xffff0000u); v0[2] += __uint_as_float(hv.y << 16); v0[3] += __uint_as_float(hv.y & 0xffff0000u);
;                     v1[0] += __uint_as_float(hv.z << 16); v1[1] += __uint_as_float(hv.z & 0xffff0000u); v1[2] += __uint_as_float(hv.w << 16); v1[3] += __uint_as_float(hv.w & 0xffff0000u);
; #pragma unroll
;                     for (int e = 0; e < 4; ++e) s += v0[e] * v0[e] + v1[e] * v1[e];
;                     if (!pad) *(u32x4*)(hout + off) = pack8(v0, v1); }
.LBB0_594:
	s_or_b64 exec, exec, s[12:13]
	s_and_saveexec_b64 s[12:13], s[56:57]
	v_cmp_gt_i32_e32 vcc, 48, v83
	s_orn2_b64 s[54:55], vcc, exec
	s_or_b64 exec, exec, s[12:13]
	v_ashrrev_i32_e32 v83, 31, v82
	v_lshlrev_b64 v[84:85], 10, v[82:83]
	v_lshl_add_u64 v[84:85], v[84:85], 0, v[140:141]
	v_lshl_add_u64 v[86:87], v[84:85], 1, s[4:5]
	s_nop 1
	s_xor_b64 s[12:13], s[54:55], -1
	v_lshl_add_u64 v[84:85], v[84:85], 1, s[0:1]
	s_and_saveexec_b64 s[56:57], s[12:13]
	s_cbranch_execz .LBB0_598
	v_cvt_pk_bf16_f32 v88, v78, v79
	v_cvt_pk_bf16_f32 v89, v80, v81
	v_cvt_pk_bf16_f32 v90, v74, v75
	v_cvt_pk_bf16_f32 v91, v76, v77
	global_store_dwordx4 v[84:85], v[88:91], off
.LBB0_598:
	s_or_b64 exec, exec, s[56:57]
	s_nop 1
	s_and_saveexec_b64 s[56:57], s[12:13]
	s_cbranch_execz .LBB0_600
	v_cvt_pk_bf16_f32 v86, v70, v71
	v_cvt_pk_bf16_f32 v87, v72, v73
	v_cvt_pk_bf16_f32 v88, v66, v67
	v_cvt_pk_bf16_f32 v89, v68, v69
	global_store_dwordx4 v[84:85], v[86:89], off offset:256

; __device__ __forceinline__ u32x4 pack8(const f32x4 a, const f32x4 b) { u32x4 w; w.x = cvt_pk_bf16(a[0], a[1]); w.y = cvt_pk_bf16(a[2], a[3]); w.z = cvt_pk_bf16(b[0], b[1]); w.w = cvt_pk_bf16(b[2], b[3]); return w; }
;     __device__ __forceinline__ void operator()(const f32x4 (&acc)[2][2][4][2], const Unit& u, int wr, int wc, int fr, int fq) const {
;     ...
;             for (int m = 0; m < 4; ++m) { const int row = row0 + u.pm * 256 + ai * 128 + wr * 64 + m * 16 + fr; const bool pad = row_is_pad(row); float s = 0.f;
; #pragma unroll
;                 for (int bj = 0; bj < 2; ++bj) { const size_t off = (size_t)row * 1024 + col0 + bj * 128; const u32x4 hv = __builtin_nontemporal_load((const u32x4*)(hin + off));
;                     f32x4 v0 = acc[ai][bj][m][0], v1 = acc[ai][bj][m][1];
;                     v0[0] += __uint_as_float(hv.x << 16); v0[1] += __uint_as_float(hv.x & 0xffff0000u); v0[2] += __uint_as_float(hv.y << 16); v0[3] += __uint_as_float(hv.y & 0xffff0000u);
;                     v1[0] += __uint_as_float(hv.z << 16); v1[1] += __uint_as_float(hv.z & 0xffff0000u); v1[2] += __uint_as_float(hv.w << 16); v1[3] += __uint_as_float(hv.w & 0xffff0000u);
; #pragma unroll
;                     for (int e = 0; e < 4; ++e) s += v0[e] * v0[e] + v1[e] * v1[e];
;                     if (!pad) *(u32x4*)(hout + off) = pack8(v0, v1); }
.LBB0_608:
	s_or_b64 exec, exec, s[12:13]
	s_and_saveexec_b64 s[12:13], s[56:57]
	v_cmp_gt_i32_e32 vcc, 48, v67
	s_orn2_b64 s[54:55], vcc, exec
	s_or_b64 exec, exec, s[12:13]
	v_ashrrev_i32_e32 v67, 31, v66
	v_lshlrev_b64 v[68:69], 10, v[66:67]
	v_lshl_add_u64 v[68:69], v[68:69], 0, v[140:141]
	v_lshl_add_u64 v[70:71], v[68:69], 1, s[4:5]
	s_nop 1
	s_xor_b64 s[12:13], s[54:55], -1
	v_lshl_add_u64 v[68:69], v[68:69], 1, s[0:1]
	s_and_saveexec_b64 s[56:57], s[12:13]
	s_cbranch_execz .LBB0_612
	v_cvt_pk_bf16_f32 v72, v62, v63
	v_cvt_pk_bf16_f32 v73, v64, v65
	v_cvt_pk_bf16_f32 v74, v58, v59
	v_cvt_pk_bf16_f32 v75, v60, v61
	global_store_dwordx4 v[68:69], v[72:75], off
.LBB0_612:
	s_or_b64 exec, exec, s[56:57]
	s_nop 1
	s_and_saveexec_b64 s[56:57], s[12:13]
	s_cbranch_execz .LBB0_614
	v_cvt_pk_bf16_f32 v70, v54, v55
	v_cvt_pk_bf16_f32 v71, v56, v57
	v_cvt_pk_bf16_f32 v72, v50, v51
	v_cvt_pk_bf16_f32 v73, v52, v53
	global_store_dwordx4 v[68:69], v[70:73], off offset:256

; __device__ __forceinline__ u32x4 pack8(const f32x4 a, const f32x4 b) { u32x4 w; w.x = cvt_pk_bf16(a[0], a[1]); w.y = cvt_pk_bf16(a[2], a[3]); w.z = cvt_pk_bf16(b[0], b[1]); w.w = cvt_pk_bf16(b[2], b[3]); return w; }
;     __device__ __forceinline__ void operator()(const f32x4 (&acc)[2][2][4][2], const Unit& u, int wr, int wc, int fr, int fq) const {
;     ...
;             for (int m = 0; m < 4; ++m) { const int row = row0 + u.pm * 256 + ai * 128 + wr * 64 + m * 16 + fr; const bool pad = row_is_pad(row); float s = 0.f;
; #pragma unroll
;                 for (int bj = 0; bj < 2; ++bj) { const size_t off = (size_t)row * 1024 + col0 + bj * 128; const u32x4 hv = __builtin_nontemporal_load((const u32x4*)(hin + off));
;                     f32x4 v0 = acc[ai][bj][m][0], v1 = acc[ai][bj][m][1];
;                     v0[0] += __uint_as_float(hv.x << 16); v0[1] += __uint_as_float(hv.x & 0xffff0000u); v0[2] += __uint_as_float(hv.y << 16); v0[3] += __uint_as_float(hv.y & 0xffff0000u);
;                     v1[0] += __uint_as_float(hv.z << 16); v1[1] += __uint_as_float(hv.z & 0xffff0000u); v1[2] += __uint_as_float(hv.w << 16); v1[3] += __uint_as_float(hv.w & 0xffff0000u);
; #pragma unroll
;                     for (int e = 0; e < 4; ++e) s += v0[e] * v0[e] + v1[e] * v1[e];
;                     if (!pad) *(u32x4*)(hout + off) = pack8(v0, v1); }
.LBB0_622:
	s_or_b64 exec, exec, s[12:13]
	s_and_saveexec_b64 s[12:13], s[56:57]
	v_cmp_gt_i32_e32 vcc, 48, v51
	s_orn2_b64 s[54:55], vcc, exec
	s_or_b64 exec, exec, s[12:13]
	v_ashrrev_i32_e32 v51, 31, v50
	v_lshlrev_b64 v[52:53], 10, v[50:51]
	v_lshl_add_u64 v[52:53], v[52:53], 0, v[140:141]
	v_lshl_add_u64 v[54:55], v[52:53], 1, s[4:5]
	s_nop 1
	s_xor_b64 s[12:13], s[54:55], -1
	v_lshl_add_u64 v[52:53], v[52:53], 1, s[0:1]
	s_and_saveexec_b64 s[56:57], s[12:13]
	s_cbranch_execz .LBB0_626
	v_cvt_pk_bf16_f32 v56, v46, v47
	v_cvt_pk_bf16_f32 v57, v48, v49
	v_cvt_pk_bf16_f32 v58, v42, v43
	v_cvt_pk_bf16_f32 v59, v44, v45
	global_store_dwordx4 v[52:53], v[56:59], off
.LBB0_626:
	s_or_b64 exec, exec, s[56:57]
	s_nop 1
	s_and_saveexec_b64 s[56:57], s[12:13]
	s_cbranch_execz .LBB0_628
	v_cvt_pk_bf16_f32 v54, v38, v39
	v_cvt_pk_bf16_f32 v55, v40, v41
	v_cvt_pk_bf16_f32 v56, v34, v35
	v_cvt_pk_bf16_f32 v57, v36, v37
	global_store_dwordx4 v[52:53], v[54:57], off offset:256

; __device__ __forceinline__ u32x4 pack8(const f32x4 a, const f32x4 b) { u32x4 w; w.x = cvt_pk_bf16(a[0], a[1]); w.y = cvt_pk_bf16(a[2], a[3]); w.z = cvt_pk_bf16(b[0], b[1]); w.w = cvt_pk_bf16(b[2], b[3]); return w; }
;     __device__ __forceinline__ void operator()(const f32x4 (&acc)[2][2][4][2], const Unit& u, int wr, int wc, int fr, int fq) const {
;     ...
;             for (int m = 0; m < 4; ++m) { const int row = row0 + u.pm * 256 + ai * 128 + wr * 64 + m * 16 + fr; const bool pad = row_is_pad(row); float s = 0.f;
; #pragma unroll
;                 for (int bj = 0; bj < 2; ++bj) { const size_t off = (size_t)row * 1024 + col0 + bj * 128; const u32x4 hv = __builtin_nontemporal_load((const u32x4*)(hin + off));
;                     f32x4 v0 = acc[ai][bj][m][0], v1 = acc[ai][bj][m][1];
;                     v0[0] += __uint_as_float(hv.x << 16); v0[1] += __uint_as_float(hv.x & 0xffff0000u); v0[2] += __uint_as_float(hv.y << 16); v0[3] += __uint_as_float(hv.y & 0xffff0000u);
;                     v1[0] += __uint_as_float(hv.z << 16); v1[1] += __uint_as_float(hv.z & 0xffff0000u); v1[2] += __uint_as_float(hv.w << 16); v1[3] += __uint_as_float(hv.w & 0xffff0000u);
; #pragma unroll
;                     for (int e = 0; e < 4; ++e) s += v0[e] * v0[e] + v1[e] * v1[e];
;                     if (!pad) *(u32x4*)(hout + off) = pack8(v0, v1); }
.LBB0_636:
	s_or_b64 exec, exec, s[12:13]
	s_and_saveexec_b64 s[12:13], s[56:57]
	v_cmp_gt_i32_e32 vcc, 48, v35
	s_orn2_b64 s[54:55], vcc, exec
	s_or_b64 exec, exec, s[12:13]
	v_ashrrev_i32_e32 v35, 31, v34
	v_lshlrev_b64 v[36:37], 10, v[34:35]
	v_lshl_add_u64 v[36:37], v[36:37], 0, v[140:141]
	v_lshl_add_u64 v[38:39], v[36:37], 1, s[4:5]
	s_nop 1
	s_xor_b64 s[12:13], s[54:55], -1
	v_lshl_add_u64 v[36:37], v[36:37], 1, s[0:1]
	s_and_saveexec_b64 s[56:57], s[12:13]
	s_cbranch_execz .LBB0_640
	v_cvt_pk_bf16_f32 v40, v30, v31
	v_cvt_pk_bf16_f32 v41, v32, v33
	v_cvt_pk_bf16_f32 v42, v26, v27
	v_cvt_pk_bf16_f32 v43, v28, v29
	global_store_dwordx4 v[36:37], v[40:43], off
.LBB0_640:
	s_or_b64 exec, exec, s[56:57]
	s_nop 1
	s_and_saveexec_b64 s[56:57], s[12:13]
	s_cbranch_execz .LBB0_642
	v_cvt_pk_bf16_f32 v38, v22, v23
	v_cvt_pk_bf16_f32 v39, v24, v25
	v_cvt_pk_bf16_f32 v40, v18, v19
	v_cvt_pk_bf16_f32 v41, v20, v21
	global_store_dwordx4 v[36:37], v[38:41], off offset:256

; __device__ __forceinline__ u32x4 pack8(const f32x4 a, const f32x4 b) { u32x4 w; w.x = cvt_pk_bf16(a[0], a[1]); w.y = cvt_pk_bf16(a[2], a[3]); w.z = cvt_pk_bf16(b[0], b[1]); w.w = cvt_pk_bf16(b[2], b[3]); return w; }
;     __device__ __forceinline__ void operator()(const f32x4 (&acc)[2][2][4][2], const Unit& u, int wr, int wc, int fr, int fq) const {
;     ...
;             for (int m = 0; m < 4; ++m) { const int row = row0 + u.pm * 256 + ai * 128 + wr * 64 + m * 16 + fr; const bool pad = row_is_pad(row); float s = 0.f;
; #pragma unroll
;                 for (int bj = 0; bj < 2; ++bj) { const size_t off = (size_t)row * 1024 + col0 + bj * 128; const u32x4 hv = __builtin_nontemporal_load((const u32x4*)(hin + off));
;                     f32x4 v0 = acc[ai][bj][m][0], v1 = acc[ai][bj][m][1];
;                     v0[0] += __uint_as_float(hv.x << 16); v0[1] += __uint_as_float(hv.x & 0xffff0000u); v0[2] += __uint_as_float(hv.y << 16); v0[3] += __uint_as_float(hv.y & 0xffff0000u);
;                     v1[0] += __uint_as_float(hv.z << 16); v1[1] += __uint_as_float(hv.z & 0xffff0000u); v1[2] += __uint_as_float(hv.w << 16); v1[3] += __uint_as_float(hv.w & 0xffff0000u);
; #pragma unroll
;                     for (int e = 0; e < 4; ++e) s += v0[e] * v0[e] + v1[e] * v1[e];
;                     if (!pad) *(u32x4*)(hout + off) = pack8(v0, v1); }
.LBB0_650:
	s_or_b64 exec, exec, s[12:13]
	s_and_saveexec_b64 s[12:13], s[56:57]
	v_cmp_gt_i32_e32 vcc, 48, v19
	s_orn2_b64 s[54:55], vcc, exec
	s_or_b64 exec, exec, s[12:13]
	v_ashrrev_i32_e32 v19, 31, v18
	v_lshlrev_b64 v[20:21], 10, v[18:19]
	v_lshl_add_u64 v[20:21], v[20:21], 0, v[140:141]
	v_lshl_add_u64 v[22:23], v[20:21], 1, s[4:5]
	s_nop 1
	s_xor_b64 s[12:13], s[54:55], -1
	v_lshl_add_u64 v[20:21], v[20:21], 1, s[0:1]
	s_and_saveexec_b64 s[56:57], s[12:13]
	s_cbranch_execz .LBB0_654
	v_cvt_pk_bf16_f32 v24, v14, v15
	v_cvt_pk_bf16_f32 v25, v16, v17
	v_cvt_pk_bf16_f32 v26, v10, v11
	v_cvt_pk_bf16_f32 v27, v12, v13
	global_store_dwordx4 v[20:21], v[24:27], off
.LBB0_654:
	s_or_b64 exec, exec, s[56:57]
	s_nop 1
	s_and_saveexec_b64 s[56:57], s[12:13]
	s_cbranch_execz .LBB0_656
	v_cvt_pk_bf16_f32 v22, v6, v7
	v_cvt_pk_bf16_f32 v23, v8, v9
	v_cvt_pk_bf16_f32 v24, v2, v3
	v_cvt_pk_bf16_f32 v25, v4, v5
	global_store_dwordx4 v[20:21], v[22:25], off offset:256
